# fused residual+RMSNorm epilogue of the last-layer w_o GEMM: first column group's residual loads also issued ahead (row-address computations cloned into spare registers); final FFN-out epilogue as in t
# baseline (speedup 1.0000x reference)
.LBB0_1455:
	s_add_u32 s42, s14, 0x14d80000
	s_addc_u32 s43, s15, 0
	s_lshr_b32 s0, s38, 5
	s_mulk_i32 s0, 0x2400
	s_ashr_i32 s1, s0, 31
	s_lshl_b32 s4, s27, 5
	s_lshl_b64 s[8:9], s[0:1], 2
	s_add_u32 s0, s54, s8
	s_addc_u32 s1, s31, s9
	s_lshl_b32 s5, s40, 8
	v_lshrrev_b32_e32 v112, 2, v187
	s_or_b32 s4, s5, s4
	v_and_b32_e32 v190, 12, v112
	v_or_b32_e32 v162, s4, v190
	v_ashrrev_i32_e32 v163, 31, v162
	v_lshlrev_b64 v[166:167], 2, v[162:163]
	v_lshl_add_u64 v[112:113], s[0:1], 0, v[166:167]
	s_mov_b64 s[0:1], 0x5000
	s_ashr_i32 s39, s38, 31
	v_lshl_add_u64 v[168:169], v[112:113], 0, s[0:1]
	s_movk_i32 s0, 0x5000
	v_add_co_u32_e32 v112, vcc, s0, v112
	s_lshl_b64 s[0:1], s[38:39], 20
	s_add_u32 s0, s60, s0
	v_addc_co_u32_e32 v113, vcc, 0, v113, vcc
	v_ashrrev_i32_e32 v149, 31, v148
	s_addc_u32 s1, s61, s1
	s_barrier
	global_load_dwordx4 v[144:147], v[112:113], off
	v_lshl_add_u64 v[184:185], s[0:1], 0, v[166:167]
	v_lshlrev_b64 v[112:113], 12, v[148:149]
	v_lshl_add_u64 v[170:171], v[184:185], 0, v[112:113]
	global_load_dwordx4 v[112:115], v[170:171], off
	v_or_b32_e32 v238, 16, v148
	v_ashrrev_i32_e32 v239, 31, v238
	v_lshlrev_b64 v[240:241], 12, v[238:239]
	v_lshl_add_u64 v[248:249], v[184:185], 0, v[240:241]
	global_load_dwordx4 v[192:195], v[248:249], off
	v_or_b32_e32 v238, 32, v148
	v_ashrrev_i32_e32 v239, 31, v238
	v_lshlrev_b64 v[240:241], 12, v[238:239]
	v_lshl_add_u64 v[248:249], v[184:185], 0, v[240:241]
	global_load_dwordx4 v[196:199], v[248:249], off
	v_or_b32_e32 v238, 48, v148
	v_ashrrev_i32_e32 v239, 31, v238
	v_lshlrev_b64 v[240:241], 12, v[238:239]
	v_lshl_add_u64 v[248:249], v[184:185], 0, v[240:241]
	global_load_dwordx4 v[200:203], v[248:249], off
	v_add_u32_e32 v238, 0x80, v148
	v_ashrrev_i32_e32 v239, 31, v238
	v_lshlrev_b64 v[240:241], 12, v[238:239]
	v_lshl_add_u64 v[248:249], v[184:185], 0, v[240:241]
	global_load_dwordx4 v[204:207], v[248:249], off
	v_add_u32_e32 v238, 0x90, v148
	v_ashrrev_i32_e32 v239, 31, v238
	v_lshlrev_b64 v[240:241], 12, v[238:239]
	v_lshl_add_u64 v[248:249], v[184:185], 0, v[240:241]
	global_load_dwordx4 v[214:217], v[248:249], off
	v_add_u32_e32 v238, 0xa0, v148
	v_ashrrev_i32_e32 v239, 31, v238
	v_lshlrev_b64 v[240:241], 12, v[238:239]
	v_lshl_add_u64 v[248:249], v[184:185], 0, v[240:241]
	global_load_dwordx4 v[224:227], v[248:249], off
	v_add_u32_e32 v238, 0xb0, v148
	v_ashrrev_i32_e32 v239, 31, v238
	v_lshlrev_b64 v[240:241], 12, v[238:239]
	v_lshl_add_u64 v[248:249], v[184:185], 0, v[240:241]
	global_load_dwordx4 v[228:231], v[248:249], off
	v_or_b32_e32 v164, 16, v148
	v_ashrrev_i32_e32 v165, 31, v164
	v_or_b32_e32 v160, 32, v148
	v_ashrrev_i32_e32 v161, 31, v160
	v_or_b32_e32 v158, 48, v148
	v_ashrrev_i32_e32 v159, 31, v158
	v_add_u32_e32 v150, 0x80, v148
	v_ashrrev_i32_e32 v151, 31, v150
	v_add_u32_e32 v156, 0x90, v148
	v_ashrrev_i32_e32 v157, 31, v156
	v_add_u32_e32 v152, 0xa0, v148
	v_ashrrev_i32_e32 v153, 31, v152
	v_add_u32_e32 v154, 0xb0, v148
	v_ashrrev_i32_e32 v155, 31, v154
	s_lshl_b32 s0, s27, 4
	s_add_i32 s0, s0, 0
	s_lshl_b32 s1, s26, 12
	s_add_i32 s1, s1, s0
	v_readlane_b32 s0, v253, 59
	v_and_b32_e32 v189, 63, v187
	s_mov_b32 s34, s54
	s_mov_b32 s54, s31
	v_cmp_gt_u32_e64 s[6:7], 32, v189
	s_waitcnt vmcnt(7)
	v_pk_fma_f32 v[124:125], v[108:109], v[144:145], v[112:113]
	v_lshlrev_b64 v[108:109], 12, v[164:165]
	v_lshl_add_u64 v[172:173], v[184:185], 0, v[108:109]
	v_pk_fma_f32 v[126:127], v[110:111], v[146:147], v[114:115]
	s_waitcnt vmcnt(6)
	v_pk_fma_f32 v[120:121], v[104:105], v[144:145], v[192:193]
	v_lshlrev_b64 v[104:105], 12, v[160:161]
	v_lshl_add_u64 v[174:175], v[184:185], 0, v[104:105]
	v_pk_fma_f32 v[122:123], v[106:107], v[146:147], v[194:195]
	s_waitcnt vmcnt(5)
	v_pk_fma_f32 v[116:117], v[100:101], v[144:145], v[196:197]
	v_lshlrev_b64 v[100:101], 12, v[158:159]
	v_lshl_add_u64 v[176:177], v[184:185], 0, v[100:101]
	v_pk_fma_f32 v[118:119], v[102:103], v[146:147], v[198:199]
	s_waitcnt vmcnt(4)
	v_pk_fma_f32 v[112:113], v[96:97], v[144:145], v[200:201]
	v_lshlrev_b64 v[96:97], 12, v[150:151]
	v_lshl_add_u64 v[178:179], v[184:185], 0, v[96:97]
	v_pk_fma_f32 v[114:115], v[98:99], v[146:147], v[202:203]
	s_waitcnt vmcnt(3)
	v_pk_fma_f32 v[108:109], v[92:93], v[144:145], v[204:205]
	v_lshlrev_b64 v[92:93], 12, v[156:157]
	v_lshl_add_u64 v[180:181], v[184:185], 0, v[92:93]
	v_pk_fma_f32 v[110:111], v[94:95], v[146:147], v[206:207]
	s_waitcnt vmcnt(2)
	v_pk_fma_f32 v[92:93], v[88:89], v[144:145], v[214:215]
	v_lshlrev_b64 v[88:89], 12, v[152:153]
	v_lshl_add_u64 v[182:183], v[184:185], 0, v[88:89]
	v_pk_fma_f32 v[94:95], v[90:91], v[146:147], v[216:217]
	s_waitcnt vmcnt(1)
	v_pk_fma_f32 v[88:89], v[80:81], v[144:145], v[224:225]
	v_lshlrev_b64 v[80:81], 12, v[154:155]
	v_lshl_add_u64 v[184:185], v[184:185], 0, v[80:81]
	v_pk_fma_f32 v[90:91], v[82:83], v[146:147], v[226:227]
	s_waitcnt vmcnt(0)
	v_pk_fma_f32 v[106:107], v[66:67], v[146:147], v[230:231]
	v_pk_fma_f32 v[104:105], v[64:65], v[144:145], v[228:229]
	global_store_dwordx4 v[170:171], v[124:127], off
	global_store_dwordx4 v[172:173], v[120:123], off
	global_store_dwordx4 v[174:175], v[116:119], off
	global_store_dwordx4 v[176:177], v[112:115], off
	global_store_dwordx4 v[178:179], v[108:111], off
	global_store_dwordx4 v[180:181], v[92:95], off
	global_store_dwordx4 v[182:183], v[88:91], off
	global_store_dwordx4 v[184:185], v[104:107], off
	global_load_dwordx4 v[80:83], v[168:169], off offset:64
	global_load_dwordx4 v[232:235], v[170:171], off offset:64
	global_load_dwordx4 v[192:195], v[172:173], off offset:64
	global_load_dwordx4 v[196:199], v[174:175], off offset:64
	global_load_dwordx4 v[200:203], v[176:177], off offset:64
	global_load_dwordx4 v[204:207], v[178:179], off offset:64
	global_load_dwordx4 v[214:217], v[180:181], off offset:64
	global_load_dwordx4 v[224:227], v[182:183], off offset:64
	global_load_dwordx4 v[228:231], v[184:185], off offset:64
	s_waitcnt vmcnt(7)
	v_pk_fma_f32 v[98:99], v[86:87], v[82:83], v[234:235]
	v_pk_fma_f32 v[96:97], v[84:85], v[80:81], v[232:233]
	s_waitcnt vmcnt(6)
	v_pk_fma_f32 v[102:103], v[78:79], v[82:83], v[194:195]
	v_pk_fma_f32 v[100:101], v[76:77], v[80:81], v[192:193]
	s_waitcnt vmcnt(5)
	v_pk_fma_f32 v[86:87], v[74:75], v[82:83], v[198:199]
	v_pk_fma_f32 v[84:85], v[72:73], v[80:81], v[196:197]
	s_waitcnt vmcnt(4)
	v_pk_fma_f32 v[70:71], v[70:71], v[82:83], v[202:203]
	v_pk_fma_f32 v[68:69], v[68:69], v[80:81], v[200:201]
	s_waitcnt vmcnt(3)
	v_pk_fma_f32 v[62:63], v[62:63], v[82:83], v[206:207]
	v_pk_fma_f32 v[60:61], v[60:61], v[80:81], v[204:205]
	s_waitcnt vmcnt(2)
	v_pk_fma_f32 v[66:67], v[58:59], v[82:83], v[216:217]
	v_pk_fma_f32 v[64:65], v[56:57], v[80:81], v[214:215]
	s_waitcnt vmcnt(1)
	v_pk_fma_f32 v[58:59], v[54:55], v[82:83], v[226:227]
	v_pk_fma_f32 v[56:57], v[52:53], v[80:81], v[224:225]
	s_waitcnt vmcnt(0)
	v_pk_fma_f32 v[78:79], v[42:43], v[82:83], v[230:231]
	v_pk_fma_f32 v[76:77], v[40:41], v[80:81], v[228:229]
	global_store_dwordx4 v[170:171], v[96:99], off offset:64
	global_store_dwordx4 v[172:173], v[100:103], off offset:64
	global_store_dwordx4 v[174:175], v[84:87], off offset:64
	global_store_dwordx4 v[176:177], v[68:71], off offset:64
	global_store_dwordx4 v[178:179], v[60:63], off offset:64
	global_store_dwordx4 v[180:181], v[64:67], off offset:64
	global_store_dwordx4 v[182:183], v[56:59], off offset:64
	global_store_dwordx4 v[184:185], v[76:79], off offset:64
	global_load_dwordx4 v[40:43], v[168:169], off offset:512
	global_load_dwordx4 v[232:235], v[170:171], off offset:512
	global_load_dwordx4 v[192:195], v[172:173], off offset:512
	global_load_dwordx4 v[196:199], v[174:175], off offset:512
	global_load_dwordx4 v[200:203], v[176:177], off offset:512
	global_load_dwordx4 v[204:207], v[178:179], off offset:512
	global_load_dwordx4 v[214:217], v[180:181], off offset:512
	global_load_dwordx4 v[224:227], v[182:183], off offset:512
	global_load_dwordx4 v[228:231], v[184:185], off offset:512
	s_waitcnt vmcnt(7)
	v_pk_fma_f32 v[74:75], v[50:51], v[42:43], v[234:235]
	v_pk_fma_f32 v[72:73], v[48:49], v[40:41], v[232:233]
	s_waitcnt vmcnt(6)
	v_pk_fma_f32 v[82:83], v[46:47], v[42:43], v[194:195]
	v_pk_fma_f32 v[80:81], v[44:45], v[40:41], v[192:193]
	s_waitcnt vmcnt(5)
	v_pk_fma_f32 v[54:55], v[38:39], v[42:43], v[198:199]
	v_pk_fma_f32 v[52:53], v[36:37], v[40:41], v[196:197]
	s_waitcnt vmcnt(4)
	v_pk_fma_f32 v[50:51], v[34:35], v[42:43], v[202:203]
	v_pk_fma_f32 v[48:49], v[32:33], v[40:41], v[200:201]
	s_waitcnt vmcnt(3)
	v_pk_fma_f32 v[38:39], v[26:27], v[42:43], v[206:207]
	v_pk_fma_f32 v[36:37], v[24:25], v[40:41], v[204:205]
	s_waitcnt vmcnt(2)
	v_pk_fma_f32 v[46:47], v[22:23], v[42:43], v[216:217]
	v_pk_fma_f32 v[44:45], v[20:21], v[40:41], v[214:215]
	s_waitcnt vmcnt(1)
	v_pk_fma_f32 v[34:35], v[18:19], v[42:43], v[226:227]
	v_pk_fma_f32 v[32:33], v[16:17], v[40:41], v[224:225]
	s_waitcnt vmcnt(0)
	v_pk_fma_f32 v[42:43], v[14:15], v[42:43], v[230:231]
	v_pk_fma_f32 v[40:41], v[12:13], v[40:41], v[228:229]
	global_store_dwordx4 v[170:171], v[72:75], off offset:512
	global_store_dwordx4 v[172:173], v[80:83], off offset:512
	global_store_dwordx4 v[174:175], v[52:55], off offset:512
	global_store_dwordx4 v[176:177], v[48:51], off offset:512
	global_store_dwordx4 v[178:179], v[36:39], off offset:512
	global_store_dwordx4 v[180:181], v[44:47], off offset:512
	global_store_dwordx4 v[182:183], v[32:35], off offset:512
	global_store_dwordx4 v[184:185], v[40:43], off offset:512
	global_load_dwordx4 v[144:147], v[168:169], off offset:576
	global_load_dwordx4 v[232:235], v[170:171], off offset:576
	global_load_dwordx4 v[192:195], v[172:173], off offset:576
	global_load_dwordx4 v[196:199], v[174:175], off offset:576
	global_load_dwordx4 v[200:203], v[176:177], off offset:576
	global_load_dwordx4 v[204:207], v[178:179], off offset:576
	global_load_dwordx4 v[214:217], v[180:181], off offset:576
	global_load_dwordx4 v[224:227], v[182:183], off offset:576
	global_load_dwordx4 v[228:231], v[184:185], off offset:576
	s_waitcnt vmcnt(7)
	v_pk_fma_f32 v[30:31], v[30:31], v[146:147], v[234:235]
	v_pk_fma_f32 v[28:29], v[28:29], v[144:145], v[232:233]
	s_waitcnt vmcnt(6)
	v_pk_fma_f32 v[26:27], v[142:143], v[146:147], v[194:195]
	v_pk_fma_f32 v[24:25], v[140:141], v[144:145], v[192:193]
	s_waitcnt vmcnt(5)
	v_pk_fma_f32 v[22:23], v[138:139], v[146:147], v[198:199]
	v_pk_fma_f32 v[20:21], v[136:137], v[144:145], v[196:197]
	s_waitcnt vmcnt(4)
	v_pk_fma_f32 v[18:19], v[134:135], v[146:147], v[202:203]
	v_pk_fma_f32 v[16:17], v[132:133], v[144:145], v[200:201]
	v_mul_f32_e32 v132, v103, v103
	v_fmac_f32_e32 v132, v102, v102
	global_store_dwordx4 v[170:171], v[28:31], off offset:576
	global_store_dwordx4 v[172:173], v[24:27], off offset:576
	global_store_dwordx4 v[174:175], v[20:23], off offset:576
	global_store_dwordx4 v[176:177], v[16:19], off offset:576
	s_waitcnt vmcnt(7)
	v_pk_fma_f32 v[14:15], v[130:131], v[146:147], v[206:207]
	v_pk_fma_f32 v[12:13], v[128:129], v[144:145], v[204:205]
	s_waitcnt vmcnt(0)
	v_pk_fma_f32 v[10:11], v[10:11], v[146:147], v[216:217]
	v_pk_fma_f32 v[8:9], v[8:9], v[144:145], v[214:215]
	s_waitcnt vmcnt(0)
	v_pk_fma_f32 v[6:7], v[6:7], v[146:147], v[226:227]
	v_pk_fma_f32 v[4:5], v[4:5], v[144:145], v[224:225]
	s_waitcnt vmcnt(0)
	v_pk_fma_f32 v[0:1], v[0:1], v[144:145], v[228:229]
	v_mul_f32_e32 v128, v125, v125
	v_mul_f32_e32 v129, v127, v127
	v_fmac_f32_e32 v128, v124, v124
	v_fmac_f32_e32 v129, v126, v126
	v_pk_fma_f32 v[2:3], v[2:3], v[146:147], v[230:231]
	v_add_f32_e32 v128, v128, v129
	v_mul_f32_e32 v129, v97, v97
	v_mul_f32_e32 v130, v99, v99
	v_fmac_f32_e32 v129, v96, v96
	v_fmac_f32_e32 v130, v98, v98
	v_add_f32_e32 v129, v129, v130
	v_add_f32_e32 v128, v128, v129
	v_mul_f32_e32 v129, v73, v73
	v_mul_f32_e32 v130, v75, v75
	v_fmac_f32_e32 v129, v72, v72
	v_fmac_f32_e32 v130, v74, v74
	v_add_f32_e32 v129, v129, v130
	v_add_f32_e32 v128, v128, v129
	v_mul_f32_e32 v129, v29, v29
	v_mul_f32_e32 v130, v31, v31
	v_fmac_f32_e32 v129, v28, v28
	v_fmac_f32_e32 v130, v30, v30
	v_add_f32_e32 v129, v129, v130
	v_mul_f32_e32 v130, v121, v121
	v_mul_f32_e32 v131, v123, v123
	v_fmac_f32_e32 v130, v120, v120
	v_fmac_f32_e32 v131, v122, v122
	v_add_f32_e32 v130, v130, v131
	v_mul_f32_e32 v131, v101, v101
	v_fmac_f32_e32 v131, v100, v100
	v_add_f32_e32 v131, v131, v132
	v_add_f32_e32 v130, v130, v131
	v_mul_f32_e32 v131, v81, v81
	v_mul_f32_e32 v132, v83, v83
	v_fmac_f32_e32 v131, v80, v80
	v_fmac_f32_e32 v132, v82, v82
	v_add_f32_e32 v131, v131, v132
	v_add_f32_e32 v130, v130, v131
	v_mul_f32_e32 v131, v25, v25
	v_mul_f32_e32 v132, v27, v27
	v_fmac_f32_e32 v131, v24, v24
	v_fmac_f32_e32 v132, v26, v26
	v_add_f32_e32 v131, v131, v132
	global_store_dwordx4 v[178:179], v[12:15], off offset:576
	global_store_dwordx4 v[180:181], v[8:11], off offset:576
	global_store_dwordx4 v[182:183], v[4:7], off offset:576
	global_store_dwordx4 v[184:185], v[0:3], off offset:576
	v_add_f32_e32 v129, v128, v129
	v_add3_u32 v128, s1, v190, v188
	v_add_f32_e32 v130, v130, v131
	ds_write2st64_b32 v128, v129, v130 offset1:4
	v_mul_f32_e32 v129, v117, v117
	v_mul_f32_e32 v130, v119, v119
	v_fmac_f32_e32 v129, v116, v116
	v_fmac_f32_e32 v130, v118, v118
	v_add_f32_e32 v129, v129, v130
	v_mul_f32_e32 v130, v85, v85
	v_mul_f32_e32 v131, v87, v87
	v_fmac_f32_e32 v130, v84, v84
	v_fmac_f32_e32 v131, v86, v86
	v_add_f32_e32 v130, v130, v131
	v_add_f32_e32 v129, v129, v130
	v_mul_f32_e32 v130, v53, v53
	v_mul_f32_e32 v131, v55, v55
	v_fmac_f32_e32 v130, v52, v52
	v_fmac_f32_e32 v131, v54, v54
	v_add_f32_e32 v130, v130, v131
	v_add_f32_e32 v129, v129, v130
	v_mul_f32_e32 v130, v21, v21
	v_mul_f32_e32 v131, v23, v23
	v_fmac_f32_e32 v130, v20, v20
	v_fmac_f32_e32 v131, v22, v22
	v_add_f32_e32 v130, v130, v131
	v_add_f32_e32 v129, v129, v130
	v_mul_f32_e32 v130, v113, v113
	v_mul_f32_e32 v131, v115, v115
	v_fmac_f32_e32 v130, v112, v112
	v_fmac_f32_e32 v131, v114, v114
	v_add_f32_e32 v130, v130, v131
	v_mul_f32_e32 v131, v69, v69
	v_mul_f32_e32 v132, v71, v71
	v_fmac_f32_e32 v131, v68, v68
	v_fmac_f32_e32 v132, v70, v70
	v_add_f32_e32 v131, v131, v132
	v_add_f32_e32 v130, v130, v131
	v_mul_f32_e32 v131, v49, v49
	v_mul_f32_e32 v132, v51, v51
	v_fmac_f32_e32 v131, v48, v48
	v_fmac_f32_e32 v132, v50, v50
	v_add_f32_e32 v131, v131, v132
	v_add_f32_e32 v130, v130, v131
	v_mul_f32_e32 v131, v17, v17
	v_mul_f32_e32 v132, v19, v19
	v_fmac_f32_e32 v131, v16, v16
	v_fmac_f32_e32 v132, v18, v18
	v_add_f32_e32 v131, v131, v132
	v_add_f32_e32 v130, v130, v131
	ds_write2st64_b32 v128, v129, v130 offset0:8 offset1:12
	v_mul_f32_e32 v129, v109, v109
	v_mul_f32_e32 v130, v111, v111
	v_fmac_f32_e32 v129, v108, v108
	v_fmac_f32_e32 v130, v110, v110
	v_add_f32_e32 v129, v129, v130
	v_mul_f32_e32 v130, v61, v61
	v_mul_f32_e32 v131, v63, v63
	v_fmac_f32_e32 v130, v60, v60
	v_fmac_f32_e32 v131, v62, v62
	v_add_f32_e32 v130, v130, v131
	v_add_f32_e32 v129, v129, v130
	v_mul_f32_e32 v130, v37, v37
	v_mul_f32_e32 v131, v39, v39
	v_fmac_f32_e32 v130, v36, v36
	v_fmac_f32_e32 v131, v38, v38
	v_add_f32_e32 v130, v130, v131
	v_add_f32_e32 v129, v129, v130
	v_mul_f32_e32 v130, v13, v13
	v_mul_f32_e32 v131, v15, v15
	v_fmac_f32_e32 v130, v12, v12
	v_fmac_f32_e32 v131, v14, v14
	v_add_f32_e32 v130, v130, v131
	v_add_f32_e32 v129, v129, v130
	v_mul_f32_e32 v130, v93, v93
	v_mul_f32_e32 v131, v95, v95
	v_fmac_f32_e32 v130, v92, v92
	v_fmac_f32_e32 v131, v94, v94
	v_add_f32_e32 v130, v130, v131
	v_mul_f32_e32 v131, v65, v65
	v_mul_f32_e32 v132, v67, v67
	v_fmac_f32_e32 v131, v64, v64
	v_fmac_f32_e32 v132, v66, v66
	v_add_f32_e32 v131, v131, v132
	v_add_f32_e32 v130, v130, v131
	v_mul_f32_e32 v131, v45, v45
	v_mul_f32_e32 v132, v47, v47
	v_fmac_f32_e32 v131, v44, v44
	v_fmac_f32_e32 v132, v46, v46
	v_add_f32_e32 v131, v131, v132
	v_add_f32_e32 v130, v130, v131
	v_mul_f32_e32 v131, v9, v9
	v_mul_f32_e32 v132, v11, v11
	v_fmac_f32_e32 v131, v8, v8
	v_fmac_f32_e32 v132, v10, v10
	v_add_f32_e32 v131, v131, v132
	v_add_f32_e32 v130, v130, v131
	ds_write2st64_b32 v128, v129, v130 offset0:32 offset1:36
	v_mul_f32_e32 v129, v89, v89
	v_mul_f32_e32 v130, v91, v91
	v_fmac_f32_e32 v129, v88, v88
	v_fmac_f32_e32 v130, v90, v90
	v_add_f32_e32 v129, v129, v130
	v_mul_f32_e32 v130, v57, v57
	v_mul_f32_e32 v131, v59, v59
	v_fmac_f32_e32 v130, v56, v56
	v_fmac_f32_e32 v131, v58, v58
	v_add_f32_e32 v130, v130, v131
	v_add_f32_e32 v129, v129, v130
	v_mul_f32_e32 v130, v33, v33
	v_mul_f32_e32 v131, v35, v35
	v_fmac_f32_e32 v130, v32, v32
	v_fmac_f32_e32 v131, v34, v34
	v_add_f32_e32 v130, v130, v131
	v_add_f32_e32 v129, v129, v130
	v_mul_f32_e32 v130, v5, v5
	v_mul_f32_e32 v131, v7, v7
	v_fmac_f32_e32 v130, v4, v4
	v_fmac_f32_e32 v131, v6, v6
	v_add_f32_e32 v130, v130, v131
	v_add_f32_e32 v129, v129, v130
	v_mul_f32_e32 v130, v105, v105
	v_mul_f32_e32 v131, v107, v107
	v_fmac_f32_e32 v130, v104, v104
	v_fmac_f32_e32 v131, v106, v106
	v_add_f32_e32 v130, v130, v131
	v_mul_f32_e32 v131, v77, v77
	v_mul_f32_e32 v132, v79, v79
	v_fmac_f32_e32 v131, v76, v76
	v_fmac_f32_e32 v132, v78, v78
	v_add_f32_e32 v131, v131, v132
	v_add_f32_e32 v130, v130, v131
	v_mul_f32_e32 v131, v41, v41
	v_mul_f32_e32 v132, v43, v43
	v_fmac_f32_e32 v131, v40, v40
	v_fmac_f32_e32 v132, v42, v42
	v_add_f32_e32 v131, v131, v132
	v_add_f32_e32 v130, v130, v131
	v_mul_f32_e32 v131, v1, v1
	v_mul_f32_e32 v132, v3, v3
	v_fmac_f32_e32 v131, v0, v0
	v_fmac_f32_e32 v132, v2, v2
	v_add_f32_e32 v131, v131, v132
	v_add_f32_e32 v130, v130, v131
	ds_write2st64_b32 v128, v129, v130 offset0:40 offset1:44
	s_waitcnt lgkmcnt(0)
	s_barrier
	v_and_b32_e32 v128, 31, v187
	v_lshl_or_b32 v130, s0, 5, v128
	v_lshl_add_u32 v128, s38, 8, v130
	s_and_saveexec_b64 s[0:1], s[6:7]
	s_cbranch_execz .LBB0_1457
	v_lshl_add_u32 v129, v130, 6, 0
	ds_read_b128 v[132:135], v129
	ds_read_b128 v[136:139], v129 offset:16
	ds_read_b128 v[140:143], v129 offset:32
	ds_read_b128 v[144:147], v129 offset:48
	s_ashr_i32 s41, s40, 31
	s_waitcnt lgkmcnt(3)
	v_add_f32_e32 v129, 0, v132
	v_add_f32_e32 v129, v129, v133
	v_add_f32_e32 v129, v129, v134
	v_add_f32_e32 v129, v129, v135
	s_waitcnt lgkmcnt(2)
	v_add_f32_e32 v129, v129, v136
	v_add_f32_e32 v129, v129, v137
	v_add_f32_e32 v129, v129, v138
	v_add_f32_e32 v129, v129, v139
	s_waitcnt lgkmcnt(1)
	v_add_f32_e32 v129, v129, v140
	v_add_f32_e32 v129, v129, v141
	v_add_f32_e32 v129, v129, v142
	v_add_f32_e32 v129, v129, v143
	s_waitcnt lgkmcnt(0)
	v_add_f32_e32 v129, v129, v144
	v_add_f32_e32 v129, v129, v145
	v_add_f32_e32 v129, v129, v146
	v_add_f32_e32 v131, v129, v147
	v_ashrrev_i32_e32 v129, 31, v128
	v_lshl_add_u64 v[132:133], v[128:129], 4, s[42:43]
	v_lshl_add_u64 v[132:133], s[40:41], 2, v[132:133]
	global_store_dword v[132:133], v131, off sc1
